# MIX lists: sample-chain partner blocks run their small attention items first and the heavy diff-sample item last (list order only)
# baseline (speedup 1.0000x reference)
.LBB0_1136:
	s_andn2_b64 vcc, exec, s[0:1]
	s_cbranch_vccnz .LBB0_1017
	v_readlane_b32 s2, v207, 49
	v_readlane_b32 s3, v207, 50
	s_mov_b64 s[0:1], -1
	s_and_b64 vcc, exec, s[2:3]
	s_cbranch_vccz .LBB0_1233
	v_readlane_b32 s0, v207, 52
	v_readlane_b32 s1, v207, 53
	s_andn2_b64 vcc, exec, s[0:1]
	v_readlane_b32 s51, v209, 0
	s_nop 3
	s_add_i32 s0, s51, 0x80
	s_sub_i32 s2, s51, 0x80
	s_cmpk_lt_u32 s51, 0x180
	s_cselect_b32 s0, s0, s2
	s_cmpk_lt_u32 s51, 0x100
	s_cselect_b32 s51, s51, s0
	s_add_i32 s0, s51, 0x80
	s_add_i32 s2, s51, 680
	s_cmpk_lt_u32 s51, 0x180
	s_cselect_b32 s0, s0, s2
	s_cmpk_lt_u32 s51, 0x100
	s_cselect_b32 s51, s51, s0
	s_mov_b32 s85, s51
	s_lshl_b32 s0, s51, 5
	v_writelane_b32 v206, s0, 51
	s_lshl_b32 s0, s51, 6
	s_add_i32 s0, s0, 0xffff5600
	v_writelane_b32 v205, s0, 31
	s_lshl_b32 s31, s51, 4
	s_addk_i32 s31, 0xc580
	s_add_i32 s30, s51, 0xfffffb58
	s_lshl_b32 s0, s51, 4
	s_add_i32 s0, s0, 0xffffb580
	v_writelane_b32 v205, s0, 29
	s_cbranch_vccz .LBB0_1152

.Lms_y2:
	s_movk_i32 s2, 936
	s_cmpk_eq_u32 s1, 680
	s_cbranch_scc1 .Lms_set
	s_cmpk_eq_u32 s1, 936
	s_cbranch_scc0 .Lms_y2b
	s_movk_i32 s2, 256
	s_cmpk_lt_u32 s0, 0x1a8
	s_cbranch_scc1 .Lms_set
	s_movk_i32 s2, 128
	s_branch .Lms_set
.Lms_y2b:
	s_movk_i32 s2, 128
	s_cmpk_eq_u32 s1, 256
	s_cbranch_scc0 .LBB0_1139
